# v92 + B1 prep weight LDS fill issued before the constant staging and first queue pop
# speedup vs baseline: 1.0088x; 1.0088x over previous
.LBB0_317:
	s_and_b64 vcc, exec, s[0:1]
	s_cbranch_vccz .LBB0_502
	s_cmp_gt_i32 s78, 0
	s_mov_b64 s[0:1], -1
	s_cbranch_scc0 .LBB0_500
	v_mov_b32_e32 v8, v133
	s_mul_i32 s0, s76, 0x680
	v_and_b32_e32 v0, 0xffffffc0, v8
	v_and_b32_e32 v3, 63, v8
	v_lshl_add_u32 v2, s76, 9, v0
	v_or_b32_e32 v2, v2, v3
	v_lshlrev_b32_e32 v64, 2, v3
	v_ashrrev_i32_e32 v3, 31, v2
	s_ashr_i32 s1, s0, 31
	v_lshlrev_b64 v[2:3], 2, v[2:3]
	v_readlane_b32 s36, v215, 26
	s_lshl_b64 s[0:1], s[0:1], 2
	v_lshl_add_u64 v[6:7], s[16:17], 0, v[2:3]
	v_readlane_b32 s37, v215, 27
	s_add_u32 s74, s14, s0
	s_waitcnt vmcnt(0) lgkmcnt(0)
	s_barrier
	global_load_dword v9, v[6:7], off
	v_readlane_b32 s40, v215, 30
	v_readlane_b32 s41, v215, 31
	v_lshl_add_u64 v[6:7], s[36:37], 0, v[2:3]
	s_addc_u32 s75, s15, s1
	v_readlane_b32 s20, v216, 4
	v_readlane_b32 s21, v216, 5
	s_lshl_b32 s2, s76, 2
	v_cmp_eq_u32_e32 vcc, 0, v133
	s_add_u32 s20, s20, s2
	s_addc_u32 s21, s21, 0
	s_and_saveexec_b64 s[28:29], vcc
	v_mov_b32_e32 v205, 1
	global_atomic_add v205, v65, v205, s[20:21] sc0
	s_mov_b64 exec, s[28:29]
	v_and_b32_e32 v218, 0xffffffc0, v133
	v_mov_b32_e32 v219, 0
	v_lshlrev_b64 v[218:219], 6, v[218:219]
	s_lshl_b64 s[20:21], s[76:77], 15
	v_lshl_add_u64 v[218:219], v[218:219], 0, s[20:21]
	v_lshlrev_b64 v[218:219], 1, v[218:219]
	v_readlane_b32 s20, v214, 33
	v_readlane_b32 s21, v214, 34
	s_nop 1
	v_lshl_add_u64 v[126:127], s[20:21], 0, v[218:219]
	v_readlane_b32 s20, v214, 35
	v_readlane_b32 s21, v214, 36
	s_nop 1
	v_lshl_add_u64 v[128:129], s[20:21], 0, v[218:219]
	v_lshrrev_b32_e32 v218, 6, v133
	v_and_b32_e32 v217, 15, v192
	v_readfirstlane_b32 s0, v218
	v_lshlrev_b32_e32 v217, 7, v217
	v_lshrrev_b32_e32 v219, 4, v192
	v_lshl_add_u32 v217, v219, 4, v217
	s_mul_i32 s0, s0, 0x3000
	s_addk_i32 s0, 0x6000
	v_mov_b32_e32 v218, v217
	v_mov_b32_e32 v219, 0
	v_lshl_add_u64 v[218:219], v[126:127], 0, v[218:219]
	s_add_i32 m0, s0, 0x0
	s_nop 0
	global_load_lds_dwordx4 v[218:219], off
	s_add_i32 m0, s0, 0x7c0
	s_nop 0
	global_load_lds_dwordx4 v[218:219], off offset:64
	s_add_i32 m0, s0, 0x800
	s_nop 0
	global_load_lds_dwordx4 v[218:219], off offset:2048
	s_add_i32 m0, s0, 0xfc0
	s_nop 0
	global_load_lds_dwordx4 v[218:219], off offset:2112
	v_add_co_u32_e32 v218, vcc, 0x1000, v218
	s_nop 1
	v_addc_co_u32_e32 v219, vcc, 0, v219, vcc
	s_add_i32 m0, s0, 0x2000
	s_nop 0
	global_load_lds_dwordx4 v[218:219], off
	s_add_i32 m0, s0, 0x27c0
	s_nop 0
	global_load_lds_dwordx4 v[218:219], off offset:64
	global_load_dwordx4 a[0:3], v[218:219], off offset:2048
	global_load_dwordx4 a[8:11], v[218:219], off offset:2112
	v_mov_b32_e32 v218, v217
	v_mov_b32_e32 v219, 0
	v_lshl_add_u64 v[218:219], v[128:129], 0, v[218:219]
	s_add_i32 m0, s0, 0x400
	s_nop 0
	global_load_lds_dwordx4 v[218:219], off
	s_add_i32 m0, s0, 0xbc0
	s_nop 0
	global_load_lds_dwordx4 v[218:219], off offset:64
	s_add_i32 m0, s0, 0xc00
	s_nop 0
	global_load_lds_dwordx4 v[218:219], off offset:2048
	s_add_i32 m0, s0, 0x13c0
	s_nop 0
	global_load_lds_dwordx4 v[218:219], off offset:2112
	v_add_co_u32_e32 v218, vcc, 0x1000, v218
	s_nop 1
	v_addc_co_u32_e32 v219, vcc, 0, v219, vcc
	s_add_i32 m0, s0, 0x2400
	s_nop 0
	global_load_lds_dwordx4 v[218:219], off
	s_add_i32 m0, s0, 0x2bc0
	s_nop 0
	global_load_lds_dwordx4 v[218:219], off offset:64
	global_load_dwordx4 a[4:7], v[218:219], off offset:2048
	global_load_dwordx4 a[12:15], v[218:219], off offset:2112
	v_lshlrev_b32_e32 v217, 4, v192
	v_add_u32_e32 v217, s0, v217
	v_lshrrev_b32_e32 v218, 6, v133
	v_lshlrev_b32_e32 v218, 7, v218
	v_lshrrev_b32_e32 v219, 4, v192
	v_lshl_add_u32 v218, v219, 3, v218
	v_add_u32_e32 v218, 0x1200, v218
	v_ashrrev_i32_e32 v1, 31, v0
	v_readlane_b32 s42, v215, 32
	v_readlane_b32 s43, v215, 33
	v_readlane_b32 s44, v215, 34
	v_readlane_b32 s45, v215, 35
	global_load_dword v10, v[6:7], off
	v_lshl_add_u64 v[6:7], s[40:41], 0, v[2:3]
	v_lshl_add_u64 v[4:5], v[0:1], 2, s[74:75]
	global_load_dword v11, v[6:7], off
	v_lshl_add_u64 v[6:7], s[42:43], 0, v[2:3]
	v_lshl_add_u64 v[2:3], s[44:45], 0, v[2:3]
	v_lshl_add_u64 v[4:5], v[4:5], 0, v[64:65]
	global_load_dword v6, v[6:7], off
	s_nop 0
	global_load_dword v7, v[2:3], off
	global_load_dword v12, v[4:5], off
	global_load_dword v13, v[4:5], off offset:2048
	v_add_co_u32_e32 v2, vcc, 0x1000, v4
	s_lshl_b64 s[0:1], s[76:77], 2
	s_nop 0
	v_addc_co_u32_e32 v3, vcc, 0, v5, vcc
	global_load_dword v2, v[2:3], off
	v_lshlrev_b32_e32 v3, 5, v8
	v_and_b32_e32 v3, 0xfffff800, v3
	v_readlane_b32 s20, v216, 4
	v_readlane_b32 s38, v215, 28
	v_readlane_b32 s39, v215, 29
	s_mov_b64 s[36:37], s[76:77]
	v_add_u32_e32 v204, 0, v3
	v_readlane_b32 s21, v216, 5
	s_add_u32 s76, s20, s0
	v_add_u32_e32 v3, v204, v64
	s_addc_u32 s77, s21, s1
	v_cmp_eq_u32_e64 s[38:39], 0, v8
	v_readlane_b32 s46, v215, 36
	v_readlane_b32 s47, v215, 37
	v_readlane_b32 s48, v215, 38
	v_readlane_b32 s49, v215, 39
	v_readlane_b32 s50, v215, 40
	v_readlane_b32 s51, v215, 41
	s_waitcnt vmcnt(6)
	ds_write2st64_b32 v3, v9, v10 offset0:32 offset1:33
	s_waitcnt vmcnt(4)
	ds_write2st64_b32 v3, v11, v6 offset0:34 offset1:35
	s_waitcnt vmcnt(2)
	ds_write2st64_b32 v3, v7, v12 offset0:36 offset1:37
	s_waitcnt vmcnt(0)
	ds_write2st64_b32 v3, v13, v2 offset0:38 offset1:39
	s_waitcnt lgkmcnt(0)
	s_barrier
	s_and_saveexec_b64 s[0:1], s[38:39]
	s_cbranch_execz .LBB0_323
	s_mov_b64 s[28:29], exec
	v_mbcnt_lo_u32_b32 v2, s28, 0
	v_mbcnt_hi_u32_b32 v2, s29, v2
	v_cmp_eq_u32_e32 vcc, 0, v2
	s_and_saveexec_b64 s[20:21], vcc
	s_cbranch_execz .LBB0_322
	s_bcnt1_i32_b64 s2, s[28:29]
	v_mov_b32_e32 v3, s2
	v_mov_b32_e32 v3, v205
